# final scale pass as a two-deep software pipeline: next item's loads in flight while the current one is processed, no wait on stores
# speedup vs baseline: 1.0070x; 1.0070x over previous
; __device__ __forceinline__ void phase_final_scale(const Params& p) {
;   const unsigned long long* rs3 = p.rowss + 3 * NTOK;
;   for (int it = blockIdx.x * NTHR + threadIdx.x; it < NTOK * (DM / 8); it += gridDim.x * NTHR) {
;     const int row = it >> 7, c8 = (it & 127) * 8;
;     const uint4 pk = *(const uint4*)(p.xb + (size_t)row * DM + c8);
;     const float rs = rsqrtf((float)rs3[row] * (1.f / (SS_FIX * DM)) + 1e-6f);
;     const float4 g0 = *(const float4*)(p.norm_final + c8), g1 = *(const float4*)(p.norm_final + c8 + 4);
.LBB0_1717:
	s_cmp_lt_i32 s74, 25
	s_waitcnt lgkmcnt(0)
	s_cselect_b64 s[0:1], -1, 0
	s_cmp_gt_i32 s75, 23
	s_cselect_b64 s[4:5], -1, 0
	s_and_b64 s[0:1], s[0:1], s[4:5]
	s_andn2_b64 vcc, exec, s[0:1]
	s_cbranch_vccnz .LBB0_1765
	s_mov_b32 s0, 0x400000
	v_cmp_gt_i32_e32 vcc, s0, v193
	s_and_saveexec_b64 s[4:5], vcc
	s_cbranch_execz .LBB0_1721
	s_load_dword s3, s[96:97], 0xb0
	s_add_u32 s0, s72, 0x190d3a00
	v_lshlrev_b32_e32 v0, 3, v192
	s_addc_u32 s1, s73, 0
	v_lshl_add_u32 v2, s2, 12, v0
	s_waitcnt lgkmcnt(0)
	s_lshl_b32 s6, s3, 9
	s_lshl_b32 s7, s3, 12
	s_mov_b64 s[2:3], 0
	v_mov_b32_e32 v1, 0
	v_mov_b32_e32 v3, 0x358637bd
	s_mov_b32 s8, 0x800000
	s_mov_b32 s9, 0x3fffff
	v_mov_b32_e32 v69, 0
	s_mov_b64 s[10:11], exec
	v_ashrrev_i32_e32 v60, 7, v193
	v_ashrrev_i32_e32 v61, 31, v60
	v_and_b32_e32 v66, 0x3f8, v2
	v_lshlrev_b64 v[62:63], 11, v[60:61]
	v_lshlrev_b32_e32 v68, 1, v66
	v_lshl_add_u64 v[64:65], v[60:61], 3, s[0:1]
	v_lshl_add_u64 v[62:63], s[54:55], 0, v[62:63]
	v_lshl_add_u64 v[62:63], v[62:63], 0, v[68:69]
	global_load_dwordx2 v[18:19], v[64:65], off
	global_load_dwordx4 v[4:7], v[62:63], off
	v_lshlrev_b32_e32 v68, 2, v66
	v_lshlrev_b64 v[16:17], 12, v[60:61]
	global_load_dwordx4 v[8:11], v68, s[20:21]
	global_load_dwordx4 v[12:15], v68, s[20:21] offset:16
	v_lshl_add_u64 v[16:17], s[22:23], 0, v[16:17]
	v_lshl_add_u64 v[16:17], v[16:17], 0, v[68:69]
	v_add_u32_e32 v24, s6, v193
	v_add_u32_e32 v25, s7, v2
	v_cmp_ge_i32_e32 vcc, s9, v24
	s_mov_b64 s[12:13], vcc
	s_cmp_eq_u64 s[12:13], 0
	s_cbranch_scc1 .Lf24_p_last
	s_mov_b64 exec, s[12:13]
	v_ashrrev_i32_e32 v60, 7, v24
	v_ashrrev_i32_e32 v61, 31, v60
	v_and_b32_e32 v66, 0x3f8, v25
	v_lshlrev_b64 v[62:63], 11, v[60:61]
	v_lshlrev_b32_e32 v68, 1, v66
	v_lshl_add_u64 v[64:65], v[60:61], 3, s[0:1]
	v_lshl_add_u64 v[62:63], s[54:55], 0, v[62:63]
	v_lshl_add_u64 v[62:63], v[62:63], 0, v[68:69]
	global_load_dwordx2 v[26:27], v[64:65], off
	global_load_dwordx4 v[28:31], v[62:63], off
	v_lshlrev_b32_e32 v68, 2, v66
	v_lshlrev_b64 v[40:41], 12, v[60:61]
	global_load_dwordx4 v[32:35], v68, s[20:21]
	global_load_dwordx4 v[36:39], v68, s[20:21] offset:16
	v_lshl_add_u64 v[40:41], s[22:23], 0, v[40:41]
	v_lshl_add_u64 v[40:41], v[40:41], 0, v[68:69]
	s_mov_b64 exec, s[10:11]
	s_waitcnt vmcnt(4)
	s_branch .Lf24_p_comp

; __device__ __forceinline__ void phase_final_scale(const Params& p) {
;     ...
;     const int row = it >> 7, c8 = (it & 127) * 8;
;     const uint4 pk = *(const uint4*)(p.xb + (size_t)row * DM + c8);
;     const float rs = rsqrtf((float)rs3[row] * (1.f / (SS_FIX * DM)) + 1e-6f);
;     const float4 g0 = *(const float4*)(p.norm_final + c8), g1 = *(const float4*)(p.norm_final + c8 + 4);
;     float4 o0, o1;
;     o0.x = __uint_as_float(pk.x << 16) * rs * g0.x; o0.y = __uint_as_float(pk.x & 0xffff0000u) * rs * g0.y;
;     o0.z = __uint_as_float(pk.y << 16) * rs * g0.z; o0.w = __uint_as_float(pk.y & 0xffff0000u) * rs * g0.w;
;     o1.x = __uint_as_float(pk.z << 16) * rs * g1.x; o1.y = __uint_as_float(pk.z & 0xffff0000u) * rs * g1.y;
;     o1.z = __uint_as_float(pk.w << 16) * rs * g1.z; o1.w = __uint_as_float(pk.w & 0xffff0000u) * rs * g1.w;
;     __builtin_nontemporal_store((f32x4){o0.x, o0.y, o0.z, o0.w}, (f32x4*)(p.out + (size_t)row * DM + c8));
;     __builtin_nontemporal_store((f32x4){o1.x, o1.y, o1.z, o1.w}, (f32x4*)(p.out + (size_t)row * DM + c8 + 4));
.Lf24_p_comp:
	v_ffbh_u32_e32 v0, v19
	v_min_u32_e32 v0, 32, v0
	v_lshlrev_b64 v[18:19], v0, v[18:19]
	v_min_u32_e32 v18, 1, v18
	v_or_b32_e32 v18, v19, v18
	v_cvt_f32_u32_e32 v18, v18
	v_sub_u32_e32 v0, 32, v0
	v_lshlrev_b32_e32 v42, 16, v4
	v_and_b32_e32 v43, 0xffff0000, v4
	v_ldexp_f32 v0, v18, v0
	v_fmamk_f32 v0, v0, 0x2e800000, v3
	v_mul_f32_e32 v18, 0x4b800000, v0
	v_cmp_gt_f32_e32 vcc, s8, v0
	v_lshlrev_b32_e32 v44, 16, v5
	v_and_b32_e32 v45, 0xffff0000, v5
	v_cndmask_b32_e32 v0, v0, v18, vcc
	v_rsq_f32_e32 v0, v0
	v_lshlrev_b32_e32 v46, 16, v6
	v_and_b32_e32 v47, 0xffff0000, v6
	v_lshlrev_b32_e32 v48, 16, v7
	v_mul_f32_e32 v18, 0x45800000, v0
	v_cndmask_b32_e32 v0, v0, v18, vcc
	v_and_b32_e32 v49, 0xffff0000, v7
	v_pk_mul_f32 v[42:43], v[0:1], v[42:43] op_sel_hi:[0,1]
	v_pk_mul_f32 v[44:45], v[0:1], v[44:45] op_sel_hi:[0,1]
	v_pk_mul_f32 v[46:47], v[0:1], v[46:47] op_sel_hi:[0,1]
	v_pk_mul_f32 v[48:49], v[0:1], v[48:49] op_sel_hi:[0,1]
	v_pk_mul_f32 v[52:53], v[8:9], v[42:43]
	v_pk_mul_f32 v[54:55], v[10:11], v[44:45]
	v_pk_mul_f32 v[56:57], v[12:13], v[46:47]
	v_pk_mul_f32 v[58:59], v[14:15], v[48:49]
	global_store_dwordx4 v[16:17], v[52:55], off nt
	global_store_dwordx4 v[16:17], v[56:59], off offset:16 nt
	s_mov_b64 s[10:11], s[12:13]
	s_mov_b64 exec, s[10:11]
	s_cbranch_execz .LBB0_1721
.Lf24_loop:
	v_add_u32_e32 v193, s6, v24
	v_add_u32_e32 v2, s7, v25
	v_cmp_ge_i32_e32 vcc, s9, v193
	s_mov_b64 s[12:13], vcc
	s_cmp_eq_u64 s[12:13], 0
	s_cbranch_scc1 .Lf24_x_last
	s_mov_b64 exec, s[12:13]
	v_ashrrev_i32_e32 v60, 7, v193
	v_ashrrev_i32_e32 v61, 31, v60
	v_and_b32_e32 v66, 0x3f8, v2
	v_lshlrev_b64 v[62:63], 11, v[60:61]
	v_lshlrev_b32_e32 v68, 1, v66
	v_lshl_add_u64 v[64:65], v[60:61], 3, s[0:1]
	v_lshl_add_u64 v[62:63], s[54:55], 0, v[62:63]
	v_lshl_add_u64 v[62:63], v[62:63], 0, v[68:69]
	global_load_dwordx2 v[18:19], v[64:65], off
	global_load_dwordx4 v[4:7], v[62:63], off
	v_lshlrev_b32_e32 v68, 2, v66
	v_lshlrev_b64 v[16:17], 12, v[60:61]
	global_load_dwordx4 v[8:11], v68, s[20:21]
	global_load_dwordx4 v[12:15], v68, s[20:21] offset:16
	v_lshl_add_u64 v[16:17], s[22:23], 0, v[16:17]
	v_lshl_add_u64 v[16:17], v[16:17], 0, v[68:69]
	s_mov_b64 exec, s[10:11]
	s_waitcnt vmcnt(6)
	s_branch .Lf24_x_comp

; __device__ __forceinline__ void phase_final_scale(const Params& p) {
;     ...
;     const int row = it >> 7, c8 = (it & 127) * 8;
;     const uint4 pk = *(const uint4*)(p.xb + (size_t)row * DM + c8);
;     const float rs = rsqrtf((float)rs3[row] * (1.f / (SS_FIX * DM)) + 1e-6f);
;     const float4 g0 = *(const float4*)(p.norm_final + c8), g1 = *(const float4*)(p.norm_final + c8 + 4);
;     float4 o0, o1;
;     o0.x = __uint_as_float(pk.x << 16) * rs * g0.x; o0.y = __uint_as_float(pk.x & 0xffff0000u) * rs * g0.y;
;     o0.z = __uint_as_float(pk.y << 16) * rs * g0.z; o0.w = __uint_as_float(pk.y & 0xffff0000u) * rs * g0.w;
;     o1.x = __uint_as_float(pk.z << 16) * rs * g1.x; o1.y = __uint_as_float(pk.z & 0xffff0000u) * rs * g1.y;
;     o1.z = __uint_as_float(pk.w << 16) * rs * g1.z; o1.w = __uint_as_float(pk.w & 0xffff0000u) * rs * g1.w;
;     __builtin_nontemporal_store((f32x4){o0.x, o0.y, o0.z, o0.w}, (f32x4*)(p.out + (size_t)row * DM + c8));
;     __builtin_nontemporal_store((f32x4){o1.x, o1.y, o1.z, o1.w}, (f32x4*)(p.out + (size_t)row * DM + c8 + 4));
.Lf24_x_comp:
	v_ffbh_u32_e32 v0, v27
	v_min_u32_e32 v0, 32, v0
	v_lshlrev_b64 v[26:27], v0, v[26:27]
	v_min_u32_e32 v26, 1, v26
	v_or_b32_e32 v26, v27, v26
	v_cvt_f32_u32_e32 v26, v26
	v_sub_u32_e32 v0, 32, v0
	v_lshlrev_b32_e32 v42, 16, v28
	v_and_b32_e32 v43, 0xffff0000, v28
	v_ldexp_f32 v0, v26, v0
	v_fmamk_f32 v0, v0, 0x2e800000, v3
	v_mul_f32_e32 v26, 0x4b800000, v0
	v_cmp_gt_f32_e32 vcc, s8, v0
	v_lshlrev_b32_e32 v44, 16, v29
	v_and_b32_e32 v45, 0xffff0000, v29
	v_cndmask_b32_e32 v0, v0, v26, vcc
	v_rsq_f32_e32 v0, v0
	v_lshlrev_b32_e32 v46, 16, v30
	v_and_b32_e32 v47, 0xffff0000, v30
	v_lshlrev_b32_e32 v48, 16, v31
	v_mul_f32_e32 v26, 0x45800000, v0
	v_cndmask_b32_e32 v0, v0, v26, vcc
	v_and_b32_e32 v49, 0xffff0000, v31
	v_pk_mul_f32 v[42:43], v[0:1], v[42:43] op_sel_hi:[0,1]
	v_pk_mul_f32 v[44:45], v[0:1], v[44:45] op_sel_hi:[0,1]
	v_pk_mul_f32 v[46:47], v[0:1], v[46:47] op_sel_hi:[0,1]
	v_pk_mul_f32 v[48:49], v[0:1], v[48:49] op_sel_hi:[0,1]
	v_pk_mul_f32 v[52:53], v[32:33], v[42:43]
	v_pk_mul_f32 v[54:55], v[34:35], v[44:45]
	v_pk_mul_f32 v[56:57], v[36:37], v[46:47]
	v_pk_mul_f32 v[58:59], v[38:39], v[48:49]
	global_store_dwordx4 v[40:41], v[52:55], off nt
	global_store_dwordx4 v[40:41], v[56:59], off offset:16 nt
	s_mov_b64 s[10:11], s[12:13]
	s_mov_b64 exec, s[10:11]
	s_cbranch_execz .LBB0_1721
	v_add_u32_e32 v24, s6, v193
	v_add_u32_e32 v25, s7, v2
	v_cmp_ge_i32_e32 vcc, s9, v24
	s_mov_b64 s[12:13], vcc
	s_cmp_eq_u64 s[12:13], 0
	s_cbranch_scc1 .Lf24_y_last
	s_mov_b64 exec, s[12:13]
	v_ashrrev_i32_e32 v60, 7, v24
	v_ashrrev_i32_e32 v61, 31, v60
	v_and_b32_e32 v66, 0x3f8, v25
	v_lshlrev_b64 v[62:63], 11, v[60:61]
	v_lshlrev_b32_e32 v68, 1, v66
	v_lshl_add_u64 v[64:65], v[60:61], 3, s[0:1]
	v_lshl_add_u64 v[62:63], s[54:55], 0, v[62:63]
	v_lshl_add_u64 v[62:63], v[62:63], 0, v[68:69]
	global_load_dwordx2 v[26:27], v[64:65], off
	global_load_dwordx4 v[28:31], v[62:63], off
	v_lshlrev_b32_e32 v68, 2, v66
	v_lshlrev_b64 v[40:41], 12, v[60:61]
	global_load_dwordx4 v[32:35], v68, s[20:21]
	global_load_dwordx4 v[36:39], v68, s[20:21] offset:16
	v_lshl_add_u64 v[40:41], s[22:23], 0, v[40:41]
	v_lshl_add_u64 v[40:41], v[40:41], 0, v[68:69]
	s_mov_b64 exec, s[10:11]
	s_waitcnt vmcnt(6)
	s_branch .Lf24_y_comp

; __device__ __forceinline__ void phase_final_scale(const Params& p) {
;     ...
;     const int row = it >> 7, c8 = (it & 127) * 8;
;     const uint4 pk = *(const uint4*)(p.xb + (size_t)row * DM + c8);
;     const float rs = rsqrtf((float)rs3[row] * (1.f / (SS_FIX * DM)) + 1e-6f);
;     const float4 g0 = *(const float4*)(p.norm_final + c8), g1 = *(const float4*)(p.norm_final + c8 + 4);
;     float4 o0, o1;
;     o0.x = __uint_as_float(pk.x << 16) * rs * g0.x; o0.y = __uint_as_float(pk.x & 0xffff0000u) * rs * g0.y;
;     o0.z = __uint_as_float(pk.y << 16) * rs * g0.z; o0.w = __uint_as_float(pk.y & 0xffff0000u) * rs * g0.w;
;     o1.x = __uint_as_float(pk.z << 16) * rs * g1.x; o1.y = __uint_as_float(pk.z & 0xffff0000u) * rs * g1.y;
;     o1.z = __uint_as_float(pk.w << 16) * rs * g1.z; o1.w = __uint_as_float(pk.w & 0xffff0000u) * rs * g1.w;
;     __builtin_nontemporal_store((f32x4){o0.x, o0.y, o0.z, o0.w}, (f32x4*)(p.out + (size_t)row * DM + c8));
;     __builtin_nontemporal_store((f32x4){o1.x, o1.y, o1.z, o1.w}, (f32x4*)(p.out + (size_t)row * DM + c8 + 4));
.Lf24_y_comp:
	v_ffbh_u32_e32 v0, v19
	v_min_u32_e32 v0, 32, v0
	v_lshlrev_b64 v[18:19], v0, v[18:19]
	v_min_u32_e32 v18, 1, v18
	v_or_b32_e32 v18, v19, v18
	v_cvt_f32_u32_e32 v18, v18
	v_sub_u32_e32 v0, 32, v0
	v_lshlrev_b32_e32 v42, 16, v4
	v_and_b32_e32 v43, 0xffff0000, v4
	v_ldexp_f32 v0, v18, v0
	v_fmamk_f32 v0, v0, 0x2e800000, v3
	v_mul_f32_e32 v18, 0x4b800000, v0
	v_cmp_gt_f32_e32 vcc, s8, v0
	v_lshlrev_b32_e32 v44, 16, v5
	v_and_b32_e32 v45, 0xffff0000, v5
	v_cndmask_b32_e32 v0, v0, v18, vcc
	v_rsq_f32_e32 v0, v0
	v_lshlrev_b32_e32 v46, 16, v6
	v_and_b32_e32 v47, 0xffff0000, v6
	v_lshlrev_b32_e32 v48, 16, v7
	v_mul_f32_e32 v18, 0x45800000, v0
	v_cndmask_b32_e32 v0, v0, v18, vcc
	v_and_b32_e32 v49, 0xffff0000, v7
	v_pk_mul_f32 v[42:43], v[0:1], v[42:43] op_sel_hi:[0,1]
	v_pk_mul_f32 v[44:45], v[0:1], v[44:45] op_sel_hi:[0,1]
	v_pk_mul_f32 v[46:47], v[0:1], v[46:47] op_sel_hi:[0,1]
	v_pk_mul_f32 v[48:49], v[0:1], v[48:49] op_sel_hi:[0,1]
	v_pk_mul_f32 v[52:53], v[8:9], v[42:43]
	v_pk_mul_f32 v[54:55], v[10:11], v[44:45]
	v_pk_mul_f32 v[56:57], v[12:13], v[46:47]
	v_pk_mul_f32 v[58:59], v[14:15], v[48:49]
	global_store_dwordx4 v[16:17], v[52:55], off nt
	global_store_dwordx4 v[16:17], v[56:59], off offset:16 nt
	s_mov_b64 s[10:11], s[12:13]
	s_mov_b64 exec, s[10:11]
	s_cbranch_execz .LBB0_1721
	s_branch .Lf24_loop
